# placement trial: v054 plus 64 B of s_nop after the scan loops (shifts prep/EW/phase-8 code by one cache line)
# speedup vs baseline: 1.0110x; 1.0110x over previous
;     ...
; #pragma unroll 1
;     for (int s6 = 0; s6 < 42; s6 += 6) {
;         if (!scan_step<GDN, NT>(F, b, h, dir, wq, lane, L, s6 + 0, St, PEND, S, Oprev, A0, A2, F1, nofin, ko)) break;
;         if (!scan_step<GDN, NT>(F, b, h, dir, wq, lane, L, s6 + 1, St, PEND, S, Oprev, A1, A0, F0, nofin, ko)) break;
;         if (!scan_step<GDN, NT>(F, b, h, dir, wq, lane, L, s6 + 2, St, PEND, S, Oprev, A2, A1, F1, nofin, ko)) break;
;         if (!scan_step<GDN, NT>(F, b, h, dir, wq, lane, L, s6 + 3, St, PEND, S, Oprev, A0, A2, F0, nofin, ko)) break;
;         if (!scan_step<GDN, NT>(F, b, h, dir, wq, lane, L, s6 + 4, St, PEND, S, Oprev, A1, A0, F1, nofin, ko)) break;
;         if (!scan_step<GDN, NT>(F, b, h, dir, wq, lane, L, s6 + 5, St, PEND, S, Oprev, A2, A1, F0, nofin, ko)) break;
;     }
.LBB0_610:
	s_nop 0
	s_nop 0
	s_nop 0
	s_nop 0
	s_nop 0
	s_nop 0
	s_nop 0
	s_nop 0
	s_nop 0
	s_nop 0
	s_nop 0
	s_nop 0
	s_nop 0
	s_nop 0
	s_nop 0
	s_nop 0
	s_mov_b64 s[10:11], 0
